# GEMM epilogues use packed f32 ops (row-scale multiply, relu^2 square, residual add): fewer VALU instructions, identical results
# speedup vs baseline: 1.1975x; 1.0018x over previous
; template <int EPI> ...
;     ...
;     if (EPI == EPI_SCALE || EPI == EPI_PLAIN || EPI == EPI_FF1) {
; #pragma unroll
;       for (int i = 0; i < 16; i++) {
;         const int rl = rbase + (i & 3) + 8 * (i >> 2);
;         const int row = m0 + rl;
;         float v0 = acc0[i], v1 = acc1[i];
;         if (EPI != EPI_PLAIN) { float rs = sRs[rl]; v0 *= rs; v1 *= rs; }
.Lgc_tailT:
	v_mfma_f32_16x16x32_bf16 v[0:3], v[194:197], v[178:181], v[0:3]
	v_mfma_f32_16x16x32_bf16 v[4:7], v[198:201], v[178:181], v[4:7]
	v_mfma_f32_16x16x32_bf16 v[8:11], v[202:205], v[178:181], v[8:11]
	v_mfma_f32_16x16x32_bf16 v[12:15], v[206:209], v[178:181], v[12:15]
	v_mfma_f32_16x16x32_bf16 v[16:19], v[210:213], v[178:181], v[16:19]
	v_mfma_f32_16x16x32_bf16 v[20:23], v[214:217], v[178:181], v[20:23]
	v_mfma_f32_16x16x32_bf16 v[24:27], v[218:221], v[178:181], v[24:27]
	v_mfma_f32_16x16x32_bf16 v[28:31], v[222:225], v[178:181], v[28:31]
	v_mfma_f32_16x16x32_bf16 v[32:35], v[194:197], v[182:185], v[32:35]
	v_mfma_f32_16x16x32_bf16 v[36:39], v[198:201], v[182:185], v[36:39]
	v_mfma_f32_16x16x32_bf16 v[40:43], v[202:205], v[182:185], v[40:43]
	v_mfma_f32_16x16x32_bf16 v[44:47], v[206:209], v[182:185], v[44:47]
	v_mfma_f32_16x16x32_bf16 v[48:51], v[210:213], v[182:185], v[48:51]
	v_mfma_f32_16x16x32_bf16 v[52:55], v[214:217], v[182:185], v[52:55]
	v_mfma_f32_16x16x32_bf16 v[56:59], v[218:221], v[182:185], v[56:59]
	v_mfma_f32_16x16x32_bf16 v[60:63], v[222:225], v[182:185], v[60:63]
	v_mfma_f32_16x16x32_bf16 v[64:67], v[194:197], v[186:189], v[64:67]
	v_mfma_f32_16x16x32_bf16 v[68:71], v[198:201], v[186:189], v[68:71]
	v_mfma_f32_16x16x32_bf16 v[72:75], v[202:205], v[186:189], v[72:75]
	v_mfma_f32_16x16x32_bf16 v[76:79], v[206:209], v[186:189], v[76:79]
	v_mfma_f32_16x16x32_bf16 v[80:83], v[210:213], v[186:189], v[80:83]
	v_mfma_f32_16x16x32_bf16 v[84:87], v[214:217], v[186:189], v[84:87]
	v_mfma_f32_16x16x32_bf16 v[88:91], v[218:221], v[186:189], v[88:91]
	v_mfma_f32_16x16x32_bf16 v[92:95], v[222:225], v[186:189], v[92:95]
	v_mfma_f32_16x16x32_bf16 v[96:99], v[194:197], v[190:193], v[96:99]
	v_mfma_f32_16x16x32_bf16 v[100:103], v[198:201], v[190:193], v[100:103]
	v_mfma_f32_16x16x32_bf16 v[104:107], v[202:205], v[190:193], v[104:107]
	v_mfma_f32_16x16x32_bf16 v[108:111], v[206:209], v[190:193], v[108:111]
	v_mfma_f32_16x16x32_bf16 v[112:115], v[210:213], v[190:193], v[112:115]
	v_mfma_f32_16x16x32_bf16 v[116:119], v[214:217], v[190:193], v[116:119]
	v_mfma_f32_16x16x32_bf16 v[120:123], v[218:221], v[190:193], v[120:123]
	v_mfma_f32_16x16x32_bf16 v[124:127], v[222:225], v[190:193], v[124:127]
	s_cmp_eq_u32 s30, 3
	s_cbranch_scc1 .Lgc_epi_res
	s_cmp_eq_u32 s30, 5
	s_cbranch_scc1 .Lgc_epi_post
	s_lshl_b32 s11, s6, 8
	s_lshl_b32 s12, s4, 6
	s_add_u32 s11, s11, s12
	v_add_u32_e32 v238, s11, v248
	v_mul_lo_u32 v230, v238, s24
	s_lshl_b32 s11, s7, 7
	s_add_u32 s11, s11, s47
	v_and_b32_e32 v239, 1, v249
	v_lshrrev_b32_e32 v240, 1, v249
	v_lshlrev_b32_e32 v239, 4, v239
	v_lshl_add_u32 v239, v240, 3, v239
	v_add_u32_e32 v239, s11, v239
	v_lshlrev_b32_e32 v239, 1, v239
	v_add_u32_e32 v230, v230, v239
	s_lshl_b32 s11, s24, 4
	v_add_u32_e32 v231, s11, v230
	v_add_u32_e32 v232, s11, v231
	v_add_u32_e32 v233, s11, v232
	s_nop 7
	s_cmp_eq_u32 s30, 4
	s_cbranch_scc1 .Lgm_norelu
	v_add_u32_e32 v239, s33, v242
	ds_read_b32 v234, v239
	ds_read_b32 v236, v239 offset:64
	ds_read_b32 v238, v239 offset:128
	ds_read_b32 v240, v239 offset:192
	s_waitcnt lgkmcnt(0)
	v_pk_mul_f32 v[0:1], v[0:1], v[234:235] op_sel_hi:[1,0]
	v_pk_mul_f32 v[2:3], v[2:3], v[234:235] op_sel_hi:[1,0]
	v_pk_mul_f32 v[4:5], v[4:5], v[234:235] op_sel_hi:[1,0]
	v_pk_mul_f32 v[6:7], v[6:7], v[234:235] op_sel_hi:[1,0]
	v_pk_mul_f32 v[8:9], v[8:9], v[234:235] op_sel_hi:[1,0]
	v_pk_mul_f32 v[10:11], v[10:11], v[234:235] op_sel_hi:[1,0]
	v_pk_mul_f32 v[12:13], v[12:13], v[234:235] op_sel_hi:[1,0]
	v_pk_mul_f32 v[14:15], v[14:15], v[234:235] op_sel_hi:[1,0]
	v_pk_mul_f32 v[16:17], v[16:17], v[234:235] op_sel_hi:[1,0]
	v_pk_mul_f32 v[18:19], v[18:19], v[234:235] op_sel_hi:[1,0]
	v_pk_mul_f32 v[20:21], v[20:21], v[234:235] op_sel_hi:[1,0]
	v_pk_mul_f32 v[22:23], v[22:23], v[234:235] op_sel_hi:[1,0]
	v_pk_mul_f32 v[24:25], v[24:25], v[234:235] op_sel_hi:[1,0]
	v_pk_mul_f32 v[26:27], v[26:27], v[234:235] op_sel_hi:[1,0]
	v_pk_mul_f32 v[28:29], v[28:29], v[234:235] op_sel_hi:[1,0]
	v_pk_mul_f32 v[30:31], v[30:31], v[234:235] op_sel_hi:[1,0]
	v_pk_mul_f32 v[32:33], v[32:33], v[236:237] op_sel_hi:[1,0]
	v_pk_mul_f32 v[34:35], v[34:35], v[236:237] op_sel_hi:[1,0]
	v_pk_mul_f32 v[36:37], v[36:37], v[236:237] op_sel_hi:[1,0]
	v_pk_mul_f32 v[38:39], v[38:39], v[236:237] op_sel_hi:[1,0]
	v_pk_mul_f32 v[40:41], v[40:41], v[236:237] op_sel_hi:[1,0]
	v_pk_mul_f32 v[42:43], v[42:43], v[236:237] op_sel_hi:[1,0]
	v_pk_mul_f32 v[44:45], v[44:45], v[236:237] op_sel_hi:[1,0]
	v_pk_mul_f32 v[46:47], v[46:47], v[236:237] op_sel_hi:[1,0]
	v_pk_mul_f32 v[48:49], v[48:49], v[236:237] op_sel_hi:[1,0]
	v_pk_mul_f32 v[50:51], v[50:51], v[236:237] op_sel_hi:[1,0]
	v_pk_mul_f32 v[52:53], v[52:53], v[236:237] op_sel_hi:[1,0]
	v_pk_mul_f32 v[54:55], v[54:55], v[236:237] op_sel_hi:[1,0]
	v_pk_mul_f32 v[56:57], v[56:57], v[236:237] op_sel_hi:[1,0]
	v_pk_mul_f32 v[58:59], v[58:59], v[236:237] op_sel_hi:[1,0]
	v_pk_mul_f32 v[60:61], v[60:61], v[236:237] op_sel_hi:[1,0]
	v_pk_mul_f32 v[62:63], v[62:63], v[236:237] op_sel_hi:[1,0]
	v_pk_mul_f32 v[64:65], v[64:65], v[238:239] op_sel_hi:[1,0]
	v_pk_mul_f32 v[66:67], v[66:67], v[238:239] op_sel_hi:[1,0]
	v_pk_mul_f32 v[68:69], v[68:69], v[238:239] op_sel_hi:[1,0]
	v_pk_mul_f32 v[70:71], v[70:71], v[238:239] op_sel_hi:[1,0]
	v_pk_mul_f32 v[72:73], v[72:73], v[238:239] op_sel_hi:[1,0]
	v_pk_mul_f32 v[74:75], v[74:75], v[238:239] op_sel_hi:[1,0]
	v_pk_mul_f32 v[76:77], v[76:77], v[238:239] op_sel_hi:[1,0]
	v_pk_mul_f32 v[78:79], v[78:79], v[238:239] op_sel_hi:[1,0]
	v_pk_mul_f32 v[80:81], v[80:81], v[238:239] op_sel_hi:[1,0]
	v_pk_mul_f32 v[82:83], v[82:83], v[238:239] op_sel_hi:[1,0]
; template <int EPI> ...
;     ...
;         if (EPI != EPI_PLAIN) { float rs = sRs[rl]; v0 *= rs; v1 *= rs; }
;         if (EPI == EPI_FF1) { v0 = fmaxf(v0, 0.f); v1 = fmaxf(v1, 0.f); v0 *= v0; v1 *= v1; }
	v_pk_mul_f32 v[84:85], v[84:85], v[238:239] op_sel_hi:[1,0]
	v_pk_mul_f32 v[86:87], v[86:87], v[238:239] op_sel_hi:[1,0]
	v_pk_mul_f32 v[88:89], v[88:89], v[238:239] op_sel_hi:[1,0]
	v_pk_mul_f32 v[90:91], v[90:91], v[238:239] op_sel_hi:[1,0]
	v_pk_mul_f32 v[92:93], v[92:93], v[238:239] op_sel_hi:[1,0]
	v_pk_mul_f32 v[94:95], v[94:95], v[238:239] op_sel_hi:[1,0]
	v_pk_mul_f32 v[96:97], v[96:97], v[240:241] op_sel_hi:[1,0]
	v_pk_mul_f32 v[98:99], v[98:99], v[240:241] op_sel_hi:[1,0]
	v_pk_mul_f32 v[100:101], v[100:101], v[240:241] op_sel_hi:[1,0]
	v_pk_mul_f32 v[102:103], v[102:103], v[240:241] op_sel_hi:[1,0]
	v_pk_mul_f32 v[104:105], v[104:105], v[240:241] op_sel_hi:[1,0]
	v_pk_mul_f32 v[106:107], v[106:107], v[240:241] op_sel_hi:[1,0]
	v_pk_mul_f32 v[108:109], v[108:109], v[240:241] op_sel_hi:[1,0]
	v_pk_mul_f32 v[110:111], v[110:111], v[240:241] op_sel_hi:[1,0]
	v_pk_mul_f32 v[112:113], v[112:113], v[240:241] op_sel_hi:[1,0]
	v_pk_mul_f32 v[114:115], v[114:115], v[240:241] op_sel_hi:[1,0]
	v_pk_mul_f32 v[116:117], v[116:117], v[240:241] op_sel_hi:[1,0]
	v_pk_mul_f32 v[118:119], v[118:119], v[240:241] op_sel_hi:[1,0]
	v_pk_mul_f32 v[120:121], v[120:121], v[240:241] op_sel_hi:[1,0]
	v_pk_mul_f32 v[122:123], v[122:123], v[240:241] op_sel_hi:[1,0]
	v_pk_mul_f32 v[124:125], v[124:125], v[240:241] op_sel_hi:[1,0]
	v_pk_mul_f32 v[126:127], v[126:127], v[240:241] op_sel_hi:[1,0]
	s_cmp_eq_u32 s30, 0
	s_cbranch_scc1 .Lgm_norelu
; template <int EPI> ...
;     ...
;         if (EPI == EPI_FF1) { v0 = fmaxf(v0, 0.f); v1 = fmaxf(v1, 0.f); v0 *= v0; v1 *= v1; }
	v_max_f32_e32 v0, 0, v0
	v_max_f32_e32 v1, 0, v1
	v_pk_mul_f32 v[0:1], v[0:1], v[0:1]
	v_max_f32_e32 v2, 0, v2
	v_max_f32_e32 v3, 0, v3
	v_pk_mul_f32 v[2:3], v[2:3], v[2:3]
	v_max_f32_e32 v4, 0, v4
	v_max_f32_e32 v5, 0, v5
	v_pk_mul_f32 v[4:5], v[4:5], v[4:5]
	v_max_f32_e32 v6, 0, v6
	v_max_f32_e32 v7, 0, v7
	v_pk_mul_f32 v[6:7], v[6:7], v[6:7]
	v_max_f32_e32 v8, 0, v8
	v_max_f32_e32 v9, 0, v9
	v_pk_mul_f32 v[8:9], v[8:9], v[8:9]
	v_max_f32_e32 v10, 0, v10
	v_max_f32_e32 v11, 0, v11
	v_pk_mul_f32 v[10:11], v[10:11], v[10:11]
	v_max_f32_e32 v12, 0, v12
	v_max_f32_e32 v13, 0, v13
	v_pk_mul_f32 v[12:13], v[12:13], v[12:13]
	v_max_f32_e32 v14, 0, v14
	v_max_f32_e32 v15, 0, v15
	v_pk_mul_f32 v[14:15], v[14:15], v[14:15]
	v_max_f32_e32 v16, 0, v16
	v_max_f32_e32 v17, 0, v17
	v_pk_mul_f32 v[16:17], v[16:17], v[16:17]
	v_max_f32_e32 v18, 0, v18
	v_max_f32_e32 v19, 0, v19
	v_pk_mul_f32 v[18:19], v[18:19], v[18:19]
	v_max_f32_e32 v20, 0, v20
	v_max_f32_e32 v21, 0, v21
	v_pk_mul_f32 v[20:21], v[20:21], v[20:21]
	v_max_f32_e32 v22, 0, v22
	v_max_f32_e32 v23, 0, v23
	v_pk_mul_f32 v[22:23], v[22:23], v[22:23]
	v_max_f32_e32 v24, 0, v24
	v_max_f32_e32 v25, 0, v25
	v_pk_mul_f32 v[24:25], v[24:25], v[24:25]
	v_max_f32_e32 v26, 0, v26
	v_max_f32_e32 v27, 0, v27
	v_pk_mul_f32 v[26:27], v[26:27], v[26:27]
	v_max_f32_e32 v28, 0, v28
	v_max_f32_e32 v29, 0, v29
	v_pk_mul_f32 v[28:29], v[28:29], v[28:29]
	v_max_f32_e32 v30, 0, v30
	v_max_f32_e32 v31, 0, v31
	v_pk_mul_f32 v[30:31], v[30:31], v[30:31]
	v_max_f32_e32 v32, 0, v32
	v_max_f32_e32 v33, 0, v33
	v_pk_mul_f32 v[32:33], v[32:33], v[32:33]
	v_max_f32_e32 v34, 0, v34
	v_max_f32_e32 v35, 0, v35
	v_pk_mul_f32 v[34:35], v[34:35], v[34:35]
	v_max_f32_e32 v36, 0, v36
	v_max_f32_e32 v37, 0, v37
	v_pk_mul_f32 v[36:37], v[36:37], v[36:37]
	v_max_f32_e32 v38, 0, v38
	v_max_f32_e32 v39, 0, v39
	v_pk_mul_f32 v[38:39], v[38:39], v[38:39]
	v_max_f32_e32 v40, 0, v40
	v_max_f32_e32 v41, 0, v41
	v_pk_mul_f32 v[40:41], v[40:41], v[40:41]
	v_max_f32_e32 v42, 0, v42
	v_max_f32_e32 v43, 0, v43
	v_pk_mul_f32 v[42:43], v[42:43], v[42:43]
	v_max_f32_e32 v44, 0, v44
	v_max_f32_e32 v45, 0, v45
	v_pk_mul_f32 v[44:45], v[44:45], v[44:45]
	v_max_f32_e32 v46, 0, v46
	v_max_f32_e32 v47, 0, v47
	v_pk_mul_f32 v[46:47], v[46:47], v[46:47]
	v_max_f32_e32 v48, 0, v48
	v_max_f32_e32 v49, 0, v49
	v_pk_mul_f32 v[48:49], v[48:49], v[48:49]
	v_max_f32_e32 v50, 0, v50
	v_max_f32_e32 v51, 0, v51
	v_pk_mul_f32 v[50:51], v[50:51], v[50:51]
	v_max_f32_e32 v52, 0, v52
	v_max_f32_e32 v53, 0, v53
	v_pk_mul_f32 v[52:53], v[52:53], v[52:53]
	v_max_f32_e32 v54, 0, v54
	v_max_f32_e32 v55, 0, v55
	v_pk_mul_f32 v[54:55], v[54:55], v[54:55]
	v_max_f32_e32 v56, 0, v56
	v_max_f32_e32 v57, 0, v57
	v_pk_mul_f32 v[56:57], v[56:57], v[56:57]
	v_max_f32_e32 v58, 0, v58
	v_max_f32_e32 v59, 0, v59
	v_pk_mul_f32 v[58:59], v[58:59], v[58:59]
	v_max_f32_e32 v60, 0, v60
	v_max_f32_e32 v61, 0, v61
	v_pk_mul_f32 v[60:61], v[60:61], v[60:61]
	v_max_f32_e32 v62, 0, v62
	v_max_f32_e32 v63, 0, v63
	v_pk_mul_f32 v[62:63], v[62:63], v[62:63]
	v_max_f32_e32 v64, 0, v64
	v_max_f32_e32 v65, 0, v65
	v_pk_mul_f32 v[64:65], v[64:65], v[64:65]
	v_max_f32_e32 v66, 0, v66
	v_max_f32_e32 v67, 0, v67
	v_pk_mul_f32 v[66:67], v[66:67], v[66:67]
	v_max_f32_e32 v68, 0, v68
	v_max_f32_e32 v69, 0, v69
	v_pk_mul_f32 v[68:69], v[68:69], v[68:69]
	v_max_f32_e32 v70, 0, v70
	v_max_f32_e32 v71, 0, v71
	v_pk_mul_f32 v[70:71], v[70:71], v[70:71]
	v_max_f32_e32 v72, 0, v72
	v_max_f32_e32 v73, 0, v73
	v_pk_mul_f32 v[72:73], v[72:73], v[72:73]
	v_max_f32_e32 v74, 0, v74
	v_max_f32_e32 v75, 0, v75
	v_pk_mul_f32 v[74:75], v[74:75], v[74:75]
	v_max_f32_e32 v76, 0, v76
	v_max_f32_e32 v77, 0, v77
	v_pk_mul_f32 v[76:77], v[76:77], v[76:77]
	v_max_f32_e32 v78, 0, v78
	v_max_f32_e32 v79, 0, v79
	v_pk_mul_f32 v[78:79], v[78:79], v[78:79]
	v_max_f32_e32 v80, 0, v80
	v_max_f32_e32 v81, 0, v81
	v_pk_mul_f32 v[80:81], v[80:81], v[80:81]
	v_max_f32_e32 v82, 0, v82
	v_max_f32_e32 v83, 0, v83
	v_pk_mul_f32 v[82:83], v[82:83], v[82:83]
	v_max_f32_e32 v84, 0, v84
	v_max_f32_e32 v85, 0, v85
	v_pk_mul_f32 v[84:85], v[84:85], v[84:85]
	v_max_f32_e32 v86, 0, v86
	v_max_f32_e32 v87, 0, v87
	v_pk_mul_f32 v[86:87], v[86:87], v[86:87]
	v_max_f32_e32 v88, 0, v88
	v_max_f32_e32 v89, 0, v89
	v_pk_mul_f32 v[88:89], v[88:89], v[88:89]
	v_max_f32_e32 v90, 0, v90
	v_max_f32_e32 v91, 0, v91
	v_pk_mul_f32 v[90:91], v[90:91], v[90:91]
	v_max_f32_e32 v92, 0, v92
	v_max_f32_e32 v93, 0, v93
	v_pk_mul_f32 v[92:93], v[92:93], v[92:93]
	v_max_f32_e32 v94, 0, v94
	v_max_f32_e32 v95, 0, v95
	v_pk_mul_f32 v[94:95], v[94:95], v[94:95]
	v_max_f32_e32 v96, 0, v96
	v_max_f32_e32 v97, 0, v97
	v_pk_mul_f32 v[96:97], v[96:97], v[96:97]
	v_max_f32_e32 v98, 0, v98
	v_max_f32_e32 v99, 0, v99
	v_pk_mul_f32 v[98:99], v[98:99], v[98:99]
	v_max_f32_e32 v100, 0, v100
	v_max_f32_e32 v101, 0, v101
	v_pk_mul_f32 v[100:101], v[100:101], v[100:101]
	v_max_f32_e32 v102, 0, v102
	v_max_f32_e32 v103, 0, v103
	v_pk_mul_f32 v[102:103], v[102:103], v[102:103]
	v_max_f32_e32 v104, 0, v104
	v_max_f32_e32 v105, 0, v105
	v_pk_mul_f32 v[104:105], v[104:105], v[104:105]
	v_max_f32_e32 v106, 0, v106
	v_max_f32_e32 v107, 0, v107
	v_pk_mul_f32 v[106:107], v[106:107], v[106:107]
	v_max_f32_e32 v108, 0, v108
	v_max_f32_e32 v109, 0, v109
	v_pk_mul_f32 v[108:109], v[108:109], v[108:109]
	v_max_f32_e32 v110, 0, v110
	v_max_f32_e32 v111, 0, v111
	v_pk_mul_f32 v[110:111], v[110:111], v[110:111]
	v_max_f32_e32 v112, 0, v112
	v_max_f32_e32 v113, 0, v113
	v_pk_mul_f32 v[112:113], v[112:113], v[112:113]
	v_max_f32_e32 v114, 0, v114
	v_max_f32_e32 v115, 0, v115
	v_pk_mul_f32 v[114:115], v[114:115], v[114:115]
	v_max_f32_e32 v116, 0, v116
	v_max_f32_e32 v117, 0, v117
	v_pk_mul_f32 v[116:117], v[116:117], v[116:117]
	v_max_f32_e32 v118, 0, v118
	v_max_f32_e32 v119, 0, v119
	v_pk_mul_f32 v[118:119], v[118:119], v[118:119]
	v_max_f32_e32 v120, 0, v120
	v_max_f32_e32 v121, 0, v121
	v_pk_mul_f32 v[120:121], v[120:121], v[120:121]
	v_max_f32_e32 v122, 0, v122
	v_max_f32_e32 v123, 0, v123
	v_pk_mul_f32 v[122:123], v[122:123], v[122:123]
	v_max_f32_e32 v124, 0, v124
	v_max_f32_e32 v125, 0, v125
	v_pk_mul_f32 v[124:125], v[124:125], v[124:125]
	v_max_f32_e32 v126, 0, v126
	v_max_f32_e32 v127, 0, v127
	v_pk_mul_f32 v[126:127], v[126:127], v[126:127]

; template <int EPI>
; __device__ __forceinline__ void gemm_phase(const Params& p, const u16* __restrict__ A, int lda, const u16* __restrict__ BT, int ldb,
;                            int K, int N, u16* __restrict__ outb, int ldo, int resid_in, int boff) {
;     ...
;     if (EPI == EPI_RES && !part_unit) {
;       const int cc0 = n0 + wn * 64 + (lane & 31);
;       float* xfq = p.out;
; #pragma unroll
;       for (int i = 0; i < 16; i++) {
;         const int row = m0 + wm * 64 + 4 * (lane >> 5) + (i & 3) + 8 * (i >> 2);
;         const float* ra = resid_in ? xrow(p, row) : (xfq + (size_t)row * 1024);
;         const float* rb = resid_in ? xrow(p, row + 32) : (xfq + (size_t)(row + 32) * 1024);
;         acc00[i] = ra[cc0]; acc01[i] = ra[cc0 + 32];
;         acc10[i] = rb[cc0]; acc11[i] = rb[cc0 + 32];
;       }
.Lgc_epi_res:
	s_lshl_b32 s11, s6, 8
	s_lshl_b32 s12, s4, 6
	s_add_u32 s11, s11, s12
	v_add_u32_e32 v238, s11, v248
	v_lshlrev_b32_e32 v243, 12, v238
	s_lshl_b32 s11, s7, 7
	v_lshl_add_u32 v239, v249, 2, s11
	v_lshlrev_b32_e32 v239, 2, v239
	v_add_u32_e32 v243, v243, v239
	v_add_u32_e32 v244, 0x10000, v243
	v_add_u32_e32 v245, 0x10000, v244
	v_add_u32_e32 v246, 0x10000, v245
	v_lshlrev_b32_e32 v247, 6, v238
	s_lshl_b32 s11, s7, 3
	v_add_u32_e32 v247, s11, v247
	s_lshl_b32 s11, s6, 8
	s_lshl_b32 s12, s4, 6
	s_add_u32 s11, s11, s12
	v_add_u32_e32 v238, s11, v248
	v_mul_lo_u32 v230, v238, s24
	s_lshl_b32 s11, s7, 7
	s_add_u32 s11, s11, s47
	v_and_b32_e32 v239, 1, v249
	v_lshrrev_b32_e32 v240, 1, v249
	v_lshlrev_b32_e32 v239, 4, v239
	v_lshl_add_u32 v239, v240, 3, v239
	v_add_u32_e32 v239, s11, v239
	v_lshlrev_b32_e32 v239, 1, v239
	v_add_u32_e32 v230, v230, v239
	s_lshl_b32 s11, s24, 4
	v_add_u32_e32 v231, s11, v230
	v_add_u32_e32 v232, s11, v231
	v_add_u32_e32 v233, s11, v232
	global_load_dwordx4 v[130:133], v243, s[48:49]
	global_load_dwordx4 v[134:137], v243, s[48:49] offset:64
	global_load_dwordx4 v[138:141], v243, s[48:49] offset:128
	global_load_dwordx4 v[142:145], v243, s[48:49] offset:192
	global_load_dwordx4 v[146:149], v243, s[48:49] offset:256
	global_load_dwordx4 v[150:153], v243, s[48:49] offset:320
	global_load_dwordx4 v[154:157], v243, s[48:49] offset:384
	global_load_dwordx4 v[158:161], v243, s[48:49] offset:448
	global_load_dwordx4 v[162:165], v244, s[48:49]
	global_load_dwordx4 v[166:169], v244, s[48:49] offset:64
	global_load_dwordx4 v[170:173], v244, s[48:49] offset:128
	global_load_dwordx4 v[174:177], v244, s[48:49] offset:192
	global_load_dwordx4 v[178:181], v244, s[48:49] offset:256
	global_load_dwordx4 v[182:185], v244, s[48:49] offset:320
	global_load_dwordx4 v[186:189], v244, s[48:49] offset:384
	global_load_dwordx4 v[190:193], v244, s[48:49] offset:448
	global_load_dwordx4 v[194:197], v245, s[48:49]
	global_load_dwordx4 v[198:201], v245, s[48:49] offset:64
	global_load_dwordx4 v[202:205], v245, s[48:49] offset:128
	global_load_dwordx4 v[206:209], v245, s[48:49] offset:192
	global_load_dwordx4 v[210:213], v245, s[48:49] offset:256
	global_load_dwordx4 v[214:217], v245, s[48:49] offset:320
	global_load_dwordx4 v[218:221], v245, s[48:49] offset:384
	global_load_dwordx4 v[222:225], v245, s[48:49] offset:448
	s_waitcnt vmcnt(23)
	v_pk_add_f32 v[0:1], v[0:1], v[130:131]
	v_pk_add_f32 v[2:3], v[2:3], v[132:133]
	global_load_dwordx4 v[130:133], v246, s[48:49]
	s_waitcnt vmcnt(23)
	v_pk_add_f32 v[4:5], v[4:5], v[134:135]
	v_pk_add_f32 v[6:7], v[6:7], v[136:137]
	global_load_dwordx4 v[134:137], v246, s[48:49] offset:64
	s_waitcnt vmcnt(23)
	v_pk_add_f32 v[8:9], v[8:9], v[138:139]
	v_pk_add_f32 v[10:11], v[10:11], v[140:141]
	global_load_dwordx4 v[138:141], v246, s[48:49] offset:128
	s_waitcnt vmcnt(23)
	v_pk_add_f32 v[12:13], v[12:13], v[142:143]
	v_pk_add_f32 v[14:15], v[14:15], v[144:145]
	global_load_dwordx4 v[142:145], v246, s[48:49] offset:192
	s_waitcnt vmcnt(23)
	v_pk_add_f32 v[16:17], v[16:17], v[146:147]
	v_pk_add_f32 v[18:19], v[18:19], v[148:149]
	global_load_dwordx4 v[146:149], v246, s[48:49] offset:256
	s_waitcnt vmcnt(23)
	v_pk_add_f32 v[20:21], v[20:21], v[150:151]
	v_pk_add_f32 v[22:23], v[22:23], v[152:153]
	global_load_dwordx4 v[150:153], v246, s[48:49] offset:320
	s_waitcnt vmcnt(23)
	v_pk_add_f32 v[24:25], v[24:25], v[154:155]
	v_pk_add_f32 v[26:27], v[26:27], v[156:157]
	global_load_dwordx4 v[154:157], v246, s[48:49] offset:384
	s_waitcnt vmcnt(23)
	v_pk_add_f32 v[28:29], v[28:29], v[158:159]
	v_pk_add_f32 v[30:31], v[30:31], v[160:161]
	global_load_dwordx4 v[158:161], v246, s[48:49] offset:448
	s_waitcnt vmcnt(23)
	v_pk_add_f32 v[32:33], v[32:33], v[162:163]
	v_pk_add_f32 v[34:35], v[34:35], v[164:165]
	s_waitcnt vmcnt(22)
	v_pk_add_f32 v[36:37], v[36:37], v[166:167]
	v_pk_add_f32 v[38:39], v[38:39], v[168:169]
	s_waitcnt vmcnt(21)
	v_pk_add_f32 v[40:41], v[40:41], v[170:171]
	v_pk_add_f32 v[42:43], v[42:43], v[172:173]
	s_waitcnt vmcnt(20)
	v_pk_add_f32 v[44:45], v[44:45], v[174:175]
	v_pk_add_f32 v[46:47], v[46:47], v[176:177]
	s_waitcnt vmcnt(19)
	v_pk_add_f32 v[48:49], v[48:49], v[178:179]
	v_pk_add_f32 v[50:51], v[50:51], v[180:181]
	s_waitcnt vmcnt(18)
	v_pk_add_f32 v[52:53], v[52:53], v[182:183]
	v_pk_add_f32 v[54:55], v[54:55], v[184:185]
	s_waitcnt vmcnt(17)
	v_pk_add_f32 v[56:57], v[56:57], v[186:187]
	v_pk_add_f32 v[58:59], v[58:59], v[188:189]
	s_waitcnt vmcnt(16)
	v_pk_add_f32 v[60:61], v[60:61], v[190:191]
	v_pk_add_f32 v[62:63], v[62:63], v[192:193]
	s_waitcnt vmcnt(15)
	v_pk_add_f32 v[64:65], v[64:65], v[194:195]
	v_pk_add_f32 v[66:67], v[66:67], v[196:197]
	s_waitcnt vmcnt(14)
	v_pk_add_f32 v[68:69], v[68:69], v[198:199]
	v_pk_add_f32 v[70:71], v[70:71], v[200:201]
	s_waitcnt vmcnt(13)
	v_pk_add_f32 v[72:73], v[72:73], v[202:203]
	v_pk_add_f32 v[74:75], v[74:75], v[204:205]
	s_waitcnt vmcnt(12)
	v_pk_add_f32 v[76:77], v[76:77], v[206:207]
	v_pk_add_f32 v[78:79], v[78:79], v[208:209]
	s_waitcnt vmcnt(11)
	v_pk_add_f32 v[80:81], v[80:81], v[210:211]
	v_pk_add_f32 v[82:83], v[82:83], v[212:213]
	s_waitcnt vmcnt(10)
	v_pk_add_f32 v[84:85], v[84:85], v[214:215]
	v_pk_add_f32 v[86:87], v[86:87], v[216:217]
	s_waitcnt vmcnt(9)
	v_pk_add_f32 v[88:89], v[88:89], v[218:219]
	v_pk_add_f32 v[90:91], v[90:91], v[220:221]
	s_waitcnt vmcnt(8)
	v_pk_add_f32 v[92:93], v[92:93], v[222:223]
	v_pk_add_f32 v[94:95], v[94:95], v[224:225]
	s_waitcnt vmcnt(7)
	v_pk_add_f32 v[96:97], v[96:97], v[130:131]
	v_pk_add_f32 v[98:99], v[98:99], v[132:133]
	s_waitcnt vmcnt(6)
; template <int EPI> ...
;     ...
;         float v0 = acc0[i], v1 = acc1[i];
;         xf[(size_t)row * 1024 + c0] = v0;
;         xf[(size_t)row * 1024 + c1] = v1;
;         outb[(size_t)row * 1024 + c0] = f2bf(v0);
;         outb[(size_t)row * 1024 + c1] = f2bf(v1);
;         float s = hsum32(v0 * v0 + v1 * v1);
;         if ((lane & 31) == 0) part[(size_t)row * 16 + nt * 2 + wn] = s;
; template <int EPI>
; __device__ __forceinline__ void gemm_phase(const Params& p, const u16* __restrict__ A, int lda, const u16* __restrict__ BT, int ldb,
;                            int K, int N, u16* __restrict__ outb, int ldo, int resid_in, int boff) {
;     ...
;     if (EPI == EPI_RES && !part_unit) {
;       const int cc0 = n0 + wn * 64 + (lane & 31);
;       float* xfq = p.out;
; #pragma unroll
;       for (int i = 0; i < 16; i++) {
;         const int row = m0 + wm * 64 + 4 * (lane >> 5) + (i & 3) + 8 * (i >> 2);
;         const float* ra = resid_in ? xrow(p, row) : (xfq + (size_t)row * 1024);
;         const float* rb = resid_in ? xrow(p, row + 32) : (xfq + (size_t)(row + 32) * 1024);
;         acc00[i] = ra[cc0]; acc01[i] = ra[cc0 + 32];
;         acc10[i] = rb[cc0]; acc11[i] = rb[cc0 + 32];
;       }
	v_pk_add_f32 v[100:101], v[100:101], v[134:135]
	v_pk_add_f32 v[102:103], v[102:103], v[136:137]
	s_waitcnt vmcnt(5)
	v_pk_add_f32 v[104:105], v[104:105], v[138:139]
	v_pk_add_f32 v[106:107], v[106:107], v[140:141]
	s_waitcnt vmcnt(4)
	v_pk_add_f32 v[108:109], v[108:109], v[142:143]
	v_pk_add_f32 v[110:111], v[110:111], v[144:145]
	s_waitcnt vmcnt(3)
	v_pk_add_f32 v[112:113], v[112:113], v[146:147]
	v_pk_add_f32 v[114:115], v[114:115], v[148:149]
	s_waitcnt vmcnt(2)
	v_pk_add_f32 v[116:117], v[116:117], v[150:151]
	v_pk_add_f32 v[118:119], v[118:119], v[152:153]
	s_waitcnt vmcnt(1)
	v_pk_add_f32 v[120:121], v[120:121], v[154:155]
	v_pk_add_f32 v[122:123], v[122:123], v[156:157]
	s_waitcnt vmcnt(0)
	v_pk_add_f32 v[124:125], v[124:125], v[158:159]
	v_pk_add_f32 v[126:127], v[126:127], v[160:161]
	global_store_dwordx4 v243, v[0:3], s[94:95]
	v_mul_f32_e32 v234, v0, v0
	v_fmac_f32_e32 v234, v1, v1
	v_fmac_f32_e32 v234, v2, v2
	v_fmac_f32_e32 v234, v3, v3
	global_store_dwordx4 v243, v[4:7], s[94:95] offset:64
	v_fmac_f32_e32 v234, v4, v4
	v_fmac_f32_e32 v234, v5, v5
	v_fmac_f32_e32 v234, v6, v6
	v_fmac_f32_e32 v234, v7, v7
	global_store_dwordx4 v243, v[8:11], s[94:95] offset:128
	v_fmac_f32_e32 v234, v8, v8
	v_fmac_f32_e32 v234, v9, v9
	v_fmac_f32_e32 v234, v10, v10
	v_fmac_f32_e32 v234, v11, v11
	global_store_dwordx4 v243, v[12:15], s[94:95] offset:192
	v_fmac_f32_e32 v234, v12, v12
	v_fmac_f32_e32 v234, v13, v13
	v_fmac_f32_e32 v234, v14, v14
	v_fmac_f32_e32 v234, v15, v15
	global_store_dwordx4 v243, v[16:19], s[94:95] offset:256
	v_fmac_f32_e32 v234, v16, v16
	v_fmac_f32_e32 v234, v17, v17
	v_fmac_f32_e32 v234, v18, v18
	v_fmac_f32_e32 v234, v19, v19
	global_store_dwordx4 v243, v[20:23], s[94:95] offset:320
	v_fmac_f32_e32 v234, v20, v20
	v_fmac_f32_e32 v234, v21, v21
	v_fmac_f32_e32 v234, v22, v22
	v_fmac_f32_e32 v234, v23, v23
	global_store_dwordx4 v243, v[24:27], s[94:95] offset:384
	v_fmac_f32_e32 v234, v24, v24
	v_fmac_f32_e32 v234, v25, v25
	v_fmac_f32_e32 v234, v26, v26
	v_fmac_f32_e32 v234, v27, v27
	global_store_dwordx4 v243, v[28:31], s[94:95] offset:448
	v_fmac_f32_e32 v234, v28, v28
	v_fmac_f32_e32 v234, v29, v29
	v_fmac_f32_e32 v234, v30, v30
	v_fmac_f32_e32 v234, v31, v31
	global_store_dwordx4 v244, v[32:35], s[94:95]
	v_mul_f32_e32 v235, v32, v32
	v_fmac_f32_e32 v235, v33, v33
	v_fmac_f32_e32 v235, v34, v34
	v_fmac_f32_e32 v235, v35, v35
	global_store_dwordx4 v244, v[36:39], s[94:95] offset:64
	v_fmac_f32_e32 v235, v36, v36
	v_fmac_f32_e32 v235, v37, v37
	v_fmac_f32_e32 v235, v38, v38
	v_fmac_f32_e32 v235, v39, v39
	global_store_dwordx4 v244, v[40:43], s[94:95] offset:128
	v_fmac_f32_e32 v235, v40, v40
	v_fmac_f32_e32 v235, v41, v41
	v_fmac_f32_e32 v235, v42, v42
	v_fmac_f32_e32 v235, v43, v43
	global_store_dwordx4 v244, v[44:47], s[94:95] offset:192
	v_fmac_f32_e32 v235, v44, v44
	v_fmac_f32_e32 v235, v45, v45
	v_fmac_f32_e32 v235, v46, v46
	v_fmac_f32_e32 v235, v47, v47
	global_store_dwordx4 v244, v[48:51], s[94:95] offset:256
	v_fmac_f32_e32 v235, v48, v48
	v_fmac_f32_e32 v235, v49, v49
	v_fmac_f32_e32 v235, v50, v50
	v_fmac_f32_e32 v235, v51, v51
	global_store_dwordx4 v244, v[52:55], s[94:95] offset:320
	v_fmac_f32_e32 v235, v52, v52
	v_fmac_f32_e32 v235, v53, v53
	v_fmac_f32_e32 v235, v54, v54
	v_fmac_f32_e32 v235, v55, v55
	global_store_dwordx4 v244, v[56:59], s[94:95] offset:384
	v_fmac_f32_e32 v235, v56, v56
	v_fmac_f32_e32 v235, v57, v57
	v_fmac_f32_e32 v235, v58, v58
	v_fmac_f32_e32 v235, v59, v59
	global_store_dwordx4 v244, v[60:63], s[94:95] offset:448
	v_fmac_f32_e32 v235, v60, v60
	v_fmac_f32_e32 v235, v61, v61
	v_fmac_f32_e32 v235, v62, v62
	v_fmac_f32_e32 v235, v63, v63
	global_store_dwordx4 v245, v[64:67], s[94:95]
	v_mul_f32_e32 v236, v64, v64
	v_fmac_f32_e32 v236, v65, v65
	v_fmac_f32_e32 v236, v66, v66
	v_fmac_f32_e32 v236, v67, v67
	global_store_dwordx4 v245, v[68:71], s[94:95] offset:64
	v_fmac_f32_e32 v236, v68, v68
	v_fmac_f32_e32 v236, v69, v69
	v_fmac_f32_e32 v236, v70, v70
	v_fmac_f32_e32 v236, v71, v71
	global_store_dwordx4 v245, v[72:75], s[94:95] offset:128
	v_fmac_f32_e32 v236, v72, v72
	v_fmac_f32_e32 v236, v73, v73
	v_fmac_f32_e32 v236, v74, v74
	v_fmac_f32_e32 v236, v75, v75
	global_store_dwordx4 v245, v[76:79], s[94:95] offset:192
	v_fmac_f32_e32 v236, v76, v76
	v_fmac_f32_e32 v236, v77, v77
	v_fmac_f32_e32 v236, v78, v78
	v_fmac_f32_e32 v236, v79, v79
	global_store_dwordx4 v245, v[80:83], s[94:95] offset:256
	v_fmac_f32_e32 v236, v80, v80
	v_fmac_f32_e32 v236, v81, v81
	v_fmac_f32_e32 v236, v82, v82
	v_fmac_f32_e32 v236, v83, v83
	global_store_dwordx4 v245, v[84:87], s[94:95] offset:320
	v_fmac_f32_e32 v236, v84, v84
	v_fmac_f32_e32 v236, v85, v85
	v_fmac_f32_e32 v236, v86, v86
	v_fmac_f32_e32 v236, v87, v87
	global_store_dwordx4 v245, v[88:91], s[94:95] offset:384
	v_fmac_f32_e32 v236, v88, v88
	v_fmac_f32_e32 v236, v89, v89
	v_fmac_f32_e32 v236, v90, v90
	v_fmac_f32_e32 v236, v91, v91
	global_store_dwordx4 v245, v[92:95], s[94:95] offset:448
	v_fmac_f32_e32 v236, v92, v92
	v_fmac_f32_e32 v236, v93, v93
	v_fmac_f32_e32 v236, v94, v94
	v_fmac_f32_e32 v236, v95, v95
	global_store_dwordx4 v246, v[96:99], s[94:95]
	v_mul_f32_e32 v237, v96, v96
	v_fmac_f32_e32 v237, v97, v97
	v_fmac_f32_e32 v237, v98, v98
	v_fmac_f32_e32 v237, v99, v99
	global_store_dwordx4 v246, v[100:103], s[94:95] offset:64
	v_fmac_f32_e32 v237, v100, v100
	v_fmac_f32_e32 v237, v101, v101
	v_fmac_f32_e32 v237, v102, v102
	v_fmac_f32_e32 v237, v103, v103
	global_store_dwordx4 v246, v[104:107], s[94:95] offset:128
	v_fmac_f32_e32 v237, v104, v104
	v_fmac_f32_e32 v237, v105, v105
	v_fmac_f32_e32 v237, v106, v106
	v_fmac_f32_e32 v237, v107, v107
	global_store_dwordx4 v246, v[108:111], s[94:95] offset:192
	v_fmac_f32_e32 v237, v108, v108
	v_fmac_f32_e32 v237, v109, v109
	v_fmac_f32_e32 v237, v110, v110
	v_fmac_f32_e32 v237, v111, v111
	global_store_dwordx4 v246, v[112:115], s[94:95] offset:256
	v_fmac_f32_e32 v237, v112, v112
	v_fmac_f32_e32 v237, v113, v113
	v_fmac_f32_e32 v237, v114, v114
	v_fmac_f32_e32 v237, v115, v115
	global_store_dwordx4 v246, v[116:119], s[94:95] offset:320
	v_fmac_f32_e32 v237, v116, v116
	v_fmac_f32_e32 v237, v117, v117
	v_fmac_f32_e32 v237, v118, v118
	v_fmac_f32_e32 v237, v119, v119
	global_store_dwordx4 v246, v[120:123], s[94:95] offset:384
	v_fmac_f32_e32 v237, v120, v120
	v_fmac_f32_e32 v237, v121, v121
	v_fmac_f32_e32 v237, v122, v122
	v_fmac_f32_e32 v237, v123, v123
	global_store_dwordx4 v246, v[124:127], s[94:95] offset:448
	v_fmac_f32_e32 v237, v124, v124
	v_fmac_f32_e32 v237, v125, v125
	v_fmac_f32_e32 v237, v126, v126
	v_fmac_f32_e32 v237, v127, v127
	s_cmp_eq_u32 s101, 19
	s_cbranch_scc1 .Lgc_res_nobf
; template <int EPI> ...
;     ...
;         outb[(size_t)row * 1024 + c0] = f2bf(v0);
;         outb[(size_t)row * 1024 + c1] = f2bf(v1);
	v_cvt_pk_bf16_f32 v0, v0, v1
	v_cvt_pk_bf16_f32 v1, v2, v3
	v_cvt_pk_bf16_f32 v2, v4, v5
	v_cvt_pk_bf16_f32 v3, v6, v7
	s_nop 1
	v_permlane16_swap_b32_e32 v0, v2
	v_permlane16_swap_b32_e32 v1, v3
	global_store_dwordx4 v230, v[0:3], s[22:23]
	v_cvt_pk_bf16_f32 v8, v8, v9
	v_cvt_pk_bf16_f32 v9, v10, v11
	v_cvt_pk_bf16_f32 v10, v12, v13
	v_cvt_pk_bf16_f32 v11, v14, v15
	s_nop 1
	v_permlane16_swap_b32_e32 v8, v10
	v_permlane16_swap_b32_e32 v9, v11
	global_store_dwordx4 v230, v[8:11], s[22:23] offset:64
	v_cvt_pk_bf16_f32 v16, v16, v17
	v_cvt_pk_bf16_f32 v17, v18, v19
	v_cvt_pk_bf16_f32 v18, v20, v21
	v_cvt_pk_bf16_f32 v19, v22, v23
	s_nop 1
	v_permlane16_swap_b32_e32 v16, v18
	v_permlane16_swap_b32_e32 v17, v19
	global_store_dwordx4 v230, v[16:19], s[22:23] offset:128
	v_cvt_pk_bf16_f32 v24, v24, v25
	v_cvt_pk_bf16_f32 v25, v26, v27
	v_cvt_pk_bf16_f32 v26, v28, v29
	v_cvt_pk_bf16_f32 v27, v30, v31
	s_nop 1
	v_permlane16_swap_b32_e32 v24, v26
	v_permlane16_swap_b32_e32 v25, v27
	global_store_dwordx4 v230, v[24:27], s[22:23] offset:192
	v_cvt_pk_bf16_f32 v32, v32, v33
	v_cvt_pk_bf16_f32 v33, v34, v35
	v_cvt_pk_bf16_f32 v34, v36, v37
	v_cvt_pk_bf16_f32 v35, v38, v39
	s_nop 1
	v_permlane16_swap_b32_e32 v32, v34
	v_permlane16_swap_b32_e32 v33, v35
	global_store_dwordx4 v231, v[32:35], s[22:23]
	v_cvt_pk_bf16_f32 v40, v40, v41
	v_cvt_pk_bf16_f32 v41, v42, v43
	v_cvt_pk_bf16_f32 v42, v44, v45
	v_cvt_pk_bf16_f32 v43, v46, v47
	s_nop 1
	v_permlane16_swap_b32_e32 v40, v42
	v_permlane16_swap_b32_e32 v41, v43
	global_store_dwordx4 v231, v[40:43], s[22:23] offset:64
	v_cvt_pk_bf16_f32 v48, v48, v49
	v_cvt_pk_bf16_f32 v49, v50, v51
	v_cvt_pk_bf16_f32 v50, v52, v53
	v_cvt_pk_bf16_f32 v51, v54, v55
	s_nop 1
	v_permlane16_swap_b32_e32 v48, v50
	v_permlane16_swap_b32_e32 v49, v51
	global_store_dwordx4 v231, v[48:51], s[22:23] offset:128
	v_cvt_pk_bf16_f32 v56, v56, v57
	v_cvt_pk_bf16_f32 v57, v58, v59
	v_cvt_pk_bf16_f32 v58, v60, v61
	v_cvt_pk_bf16_f32 v59, v62, v63
	s_nop 1
	v_permlane16_swap_b32_e32 v56, v58
	v_permlane16_swap_b32_e32 v57, v59
	global_store_dwordx4 v231, v[56:59], s[22:23] offset:192
	v_cvt_pk_bf16_f32 v64, v64, v65
	v_cvt_pk_bf16_f32 v65, v66, v67
	v_cvt_pk_bf16_f32 v66, v68, v69
	v_cvt_pk_bf16_f32 v67, v70, v71
	s_nop 1
	v_permlane16_swap_b32_e32 v64, v66
	v_permlane16_swap_b32_e32 v65, v67
	global_store_dwordx4 v232, v[64:67], s[22:23]
	v_cvt_pk_bf16_f32 v72, v72, v73
	v_cvt_pk_bf16_f32 v73, v74, v75
	v_cvt_pk_bf16_f32 v74, v76, v77
	v_cvt_pk_bf16_f32 v75, v78, v79
	s_nop 1
	v_permlane16_swap_b32_e32 v72, v74
	v_permlane16_swap_b32_e32 v73, v75
	global_store_dwordx4 v232, v[72:75], s[22:23] offset:64
	v_cvt_pk_bf16_f32 v80, v80, v81
	v_cvt_pk_bf16_f32 v81, v82, v83
	v_cvt_pk_bf16_f32 v82, v84, v85
	v_cvt_pk_bf16_f32 v83, v86, v87
	s_nop 1
	v_permlane16_swap_b32_e32 v80, v82
	v_permlane16_swap_b32_e32 v81, v83
	global_store_dwordx4 v232, v[80:83], s[22:23] offset:128
	v_cvt_pk_bf16_f32 v88, v88, v89
	v_cvt_pk_bf16_f32 v89, v90, v91
	v_cvt_pk_bf16_f32 v90, v92, v93
	v_cvt_pk_bf16_f32 v91, v94, v95
	s_nop 1
	v_permlane16_swap_b32_e32 v88, v90
	v_permlane16_swap_b32_e32 v89, v91
	global_store_dwordx4 v232, v[88:91], s[22:23] offset:192
	v_cvt_pk_bf16_f32 v96, v96, v97
	v_cvt_pk_bf16_f32 v97, v98, v99
	v_cvt_pk_bf16_f32 v98, v100, v101
	v_cvt_pk_bf16_f32 v99, v102, v103
	s_nop 1
	v_permlane16_swap_b32_e32 v96, v98
	v_permlane16_swap_b32_e32 v97, v99
	global_store_dwordx4 v233, v[96:99], s[22:23]
	v_cvt_pk_bf16_f32 v104, v104, v105
	v_cvt_pk_bf16_f32 v105, v106, v107
	v_cvt_pk_bf16_f32 v106, v108, v109
	v_cvt_pk_bf16_f32 v107, v110, v111
	s_nop 1
	v_permlane16_swap_b32_e32 v104, v106
	v_permlane16_swap_b32_e32 v105, v107
	global_store_dwordx4 v233, v[104:107], s[22:23] offset:64
	v_cvt_pk_bf16_f32 v112, v112, v113
	v_cvt_pk_bf16_f32 v113, v114, v115
	v_cvt_pk_bf16_f32 v114, v116, v117
	v_cvt_pk_bf16_f32 v115, v118, v119
	s_nop 1
	v_permlane16_swap_b32_e32 v112, v114
	v_permlane16_swap_b32_e32 v113, v115
	global_store_dwordx4 v233, v[112:115], s[22:23] offset:128
	v_cvt_pk_bf16_f32 v120, v120, v121
	v_cvt_pk_bf16_f32 v121, v122, v123
	v_cvt_pk_bf16_f32 v122, v124, v125
	v_cvt_pk_bf16_f32 v123, v126, v127
	s_nop 1
	v_permlane16_swap_b32_e32 v120, v122
	v_permlane16_swap_b32_e32 v121, v123
	global_store_dwordx4 v233, v[120:123], s[22:23] offset:192

; template <int EPI> ...
;     ...
;     if (EPI == EPI_SCALE || EPI == EPI_PLAIN || EPI == EPI_FF1) {
; #pragma unroll
;       for (int i = 0; i < 16; i++) {
;         const int rl = rbase + (i & 3) + 8 * (i >> 2);
;         const int row = m0 + rl;
;         float v0 = acc0[i], v1 = acc1[i];
;         if (EPI != EPI_PLAIN) { float rs = sRs[rl]; v0 *= rs; v1 *= rs; }
;         if (EPI == EPI_FF1) { v0 = fmaxf(v0, 0.f); v1 = fmaxf(v1, 0.f); v0 *= v0; v1 *= v1; }
.Lgc_tailW:
	v_mfma_f32_16x16x32_bf16 v[0:3], v[194:197], v[178:181], v[0:3]
	v_mfma_f32_16x16x32_bf16 v[4:7], v[198:201], v[178:181], v[4:7]
	v_mfma_f32_16x16x32_bf16 v[32:35], v[194:197], v[182:185], v[32:35]
	v_mfma_f32_16x16x32_bf16 v[36:39], v[198:201], v[182:185], v[36:39]
	v_mfma_f32_16x16x32_bf16 v[64:67], v[194:197], v[186:189], v[64:67]
	v_mfma_f32_16x16x32_bf16 v[68:71], v[198:201], v[186:189], v[68:71]
	v_mfma_f32_16x16x32_bf16 v[96:99], v[194:197], v[190:193], v[96:99]
	v_mfma_f32_16x16x32_bf16 v[100:103], v[198:201], v[190:193], v[100:103]
	s_lshl_b32 s11, s6, 8
	s_lshl_b32 s12, s4, 6
	s_add_u32 s11, s11, s12
	v_add_u32_e32 v238, s11, v248
	v_mul_lo_u32 v230, v238, s24
	s_lshl_b32 s11, s7, 7
	s_add_u32 s11, s11, s47
	v_and_b32_e32 v239, 1, v249
	v_lshrrev_b32_e32 v240, 1, v249
	v_lshlrev_b32_e32 v239, 4, v239
	v_lshl_add_u32 v239, v240, 3, v239
	v_add_u32_e32 v239, s11, v239
	v_lshlrev_b32_e32 v239, 1, v239
	v_add_u32_e32 v230, v230, v239
	s_lshl_b32 s11, s24, 4
	v_add_u32_e32 v231, s11, v230
	v_add_u32_e32 v232, s11, v231
	v_add_u32_e32 v233, s11, v232
	s_nop 7
	v_add_u32_e32 v239, s33, v242
	ds_read_b32 v234, v239
	ds_read_b32 v236, v239 offset:64
	ds_read_b32 v238, v239 offset:128
	ds_read_b32 v240, v239 offset:192
	s_waitcnt lgkmcnt(0)
	v_pk_mul_f32 v[0:1], v[0:1], v[234:235] op_sel_hi:[1,0]
	v_pk_mul_f32 v[2:3], v[2:3], v[234:235] op_sel_hi:[1,0]
	v_pk_mul_f32 v[4:5], v[4:5], v[234:235] op_sel_hi:[1,0]
	v_pk_mul_f32 v[6:7], v[6:7], v[234:235] op_sel_hi:[1,0]
	v_pk_mul_f32 v[32:33], v[32:33], v[236:237] op_sel_hi:[1,0]
	v_pk_mul_f32 v[34:35], v[34:35], v[236:237] op_sel_hi:[1,0]
	v_pk_mul_f32 v[36:37], v[36:37], v[236:237] op_sel_hi:[1,0]
	v_pk_mul_f32 v[38:39], v[38:39], v[236:237] op_sel_hi:[1,0]
	v_pk_mul_f32 v[64:65], v[64:65], v[238:239] op_sel_hi:[1,0]
	v_pk_mul_f32 v[66:67], v[66:67], v[238:239] op_sel_hi:[1,0]
	v_pk_mul_f32 v[68:69], v[68:69], v[238:239] op_sel_hi:[1,0]
	v_pk_mul_f32 v[70:71], v[70:71], v[238:239] op_sel_hi:[1,0]
	v_pk_mul_f32 v[96:97], v[96:97], v[240:241] op_sel_hi:[1,0]
	v_pk_mul_f32 v[98:99], v[98:99], v[240:241] op_sel_hi:[1,0]
	v_pk_mul_f32 v[100:101], v[100:101], v[240:241] op_sel_hi:[1,0]
	v_pk_mul_f32 v[102:103], v[102:103], v[240:241] op_sel_hi:[1,0]
	s_cmp_eq_u32 s30, 0
	s_cbranch_scc1 .Lgw_norelu
	v_max_f32_e32 v0, 0, v0
	v_max_f32_e32 v1, 0, v1
	v_pk_mul_f32 v[0:1], v[0:1], v[0:1]
	v_max_f32_e32 v2, 0, v2
	v_max_f32_e32 v3, 0, v3
	v_pk_mul_f32 v[2:3], v[2:3], v[2:3]
	v_max_f32_e32 v4, 0, v4
	v_max_f32_e32 v5, 0, v5
	v_pk_mul_f32 v[4:5], v[4:5], v[4:5]
	v_max_f32_e32 v6, 0, v6
	v_max_f32_e32 v7, 0, v7
	v_pk_mul_f32 v[6:7], v[6:7], v[6:7]
	v_max_f32_e32 v32, 0, v32
	v_max_f32_e32 v33, 0, v33
	v_pk_mul_f32 v[32:33], v[32:33], v[32:33]
	v_max_f32_e32 v34, 0, v34
	v_max_f32_e32 v35, 0, v35
	v_pk_mul_f32 v[34:35], v[34:35], v[34:35]
	v_max_f32_e32 v36, 0, v36
	v_max_f32_e32 v37, 0, v37
	v_pk_mul_f32 v[36:37], v[36:37], v[36:37]
	v_max_f32_e32 v38, 0, v38
	v_max_f32_e32 v39, 0, v39
	v_pk_mul_f32 v[38:39], v[38:39], v[38:39]
	v_max_f32_e32 v64, 0, v64
	v_max_f32_e32 v65, 0, v65
	v_pk_mul_f32 v[64:65], v[64:65], v[64:65]
	v_max_f32_e32 v66, 0, v66
	v_max_f32_e32 v67, 0, v67
	v_pk_mul_f32 v[66:67], v[66:67], v[66:67]
	v_max_f32_e32 v68, 0, v68
	v_max_f32_e32 v69, 0, v69
	v_pk_mul_f32 v[68:69], v[68:69], v[68:69]
	v_max_f32_e32 v70, 0, v70
	v_max_f32_e32 v71, 0, v71
	v_pk_mul_f32 v[70:71], v[70:71], v[70:71]
	v_max_f32_e32 v96, 0, v96
	v_max_f32_e32 v97, 0, v97
	v_pk_mul_f32 v[96:97], v[96:97], v[96:97]
	v_max_f32_e32 v98, 0, v98
	v_max_f32_e32 v99, 0, v99
	v_pk_mul_f32 v[98:99], v[98:99], v[98:99]
	v_max_f32_e32 v100, 0, v100
	v_max_f32_e32 v101, 0, v101
	v_pk_mul_f32 v[100:101], v[100:101], v[100:101]
	v_max_f32_e32 v102, 0, v102
	v_max_f32_e32 v103, 0, v103
	v_pk_mul_f32 v[102:103], v[102:103], v[102:103]
